# scan pass B output-tile loop: the six srcA LDS reads of each MFMA chain issued together with counted lgkmcnt waits (was read-wait-MFMA x6)
# speedup vs baseline: 1.0100x; 1.0013x over previous
.LBB0_630:
	v_add_u32_e32 v136, 0, v95
	v_add_u32_e32 v137, 0, v94
	ds_read_b128 v[96:99], v136
	ds_read_b128 v[128:131], v136 offset:64
	ds_read_b128 v[232:235], v136 offset:128
	ds_read_b128 v[236:239], v136 offset:192
	v_add_u32_e32 v248, 0x17600, v137
	v_add_u32_e32 v249, 0x18800, v137
	ds_read_b64_tr_b16 v[240:241], v248
	ds_read_b64_tr_b16 v[242:243], v249
	v_add_u32_e32 v248, 0x19a00, v137
	v_add_u32_e32 v249, 0x1ac00, v137
	ds_read_b64_tr_b16 v[244:245], v248
	ds_read_b64_tr_b16 v[246:247], v249
	s_brev_b32 s30, 52
	v_add_u32_e32 v94, 64, v94
	s_waitcnt lgkmcnt(7)
	v_mfma_f32_16x16x32_bf16 v[96:99], v[96:99], v[76:79], 0
	v_add_u32_e32 v95, 0x2200, v95
	s_waitcnt lgkmcnt(6)
	v_mfma_f32_16x16x32_bf16 v[96:99], v[128:131], v[80:83], v[96:99]
	s_waitcnt lgkmcnt(5)
	v_mfma_f32_16x16x32_bf16 v[96:99], v[232:235], v[84:87], v[96:99]
	s_waitcnt lgkmcnt(4)
	v_mfma_f32_16x16x32_bf16 v[96:99], v[236:239], v[88:91], v[96:99]
	s_waitcnt lgkmcnt(2)
	v_mfma_f32_16x16x32_bf16 v[96:99], v[240:243], v[68:71], v[96:99]
	s_waitcnt lgkmcnt(0)
	v_mfma_f32_16x16x32_bf16 v[96:99], v[244:247], v[72:75], v[96:99]
	v_lshl_add_u64 v[128:129], v[92:93], 0, s[0:1]
	v_add_co_u32_e32 v132, vcc, s30, v128
	s_mov_b32 s30, 0x2c001000
	s_nop 0
	v_addc_co_u32_e32 v133, vcc, 0, v129, vcc
	v_add_co_u32_e32 v134, vcc, s30, v128
	s_nop 1
	v_cvt_pk_bf16_f32 v96, v96, v97
	v_addc_co_u32_e32 v135, vcc, 0, v129, vcc
	v_cvt_pk_bf16_f32 v97, v98, v99
	global_store_dwordx2 v[134:135], v[96:97], off offset:-4096
	ds_read_b128 v[96:99], v136 offset:4352
	ds_read_b128 v[128:131], v136 offset:4416
	ds_read_b128 v[232:235], v136 offset:4480
	ds_read_b128 v[236:239], v136 offset:4544
	v_add_u32_e32 v248, 0x17620, v137
	v_add_u32_e32 v249, 0x18820, v137
	ds_read_b64_tr_b16 v[240:241], v248
	ds_read_b64_tr_b16 v[242:243], v249
	v_add_u32_e32 v248, 0x19a20, v137
	v_add_u32_e32 v249, 0x1ac20, v137
	ds_read_b64_tr_b16 v[244:245], v248
	ds_read_b64_tr_b16 v[246:247], v249
	s_waitcnt lgkmcnt(7)
	v_mfma_f32_16x16x32_bf16 v[96:99], v[96:99], v[76:79], 0
	s_add_u32 s0, s0, 64
	s_addc_u32 s1, s1, 0
	s_cmpk_eq_i32 s0, 0x80
	s_waitcnt lgkmcnt(6)
	v_mfma_f32_16x16x32_bf16 v[96:99], v[128:131], v[80:83], v[96:99]
	s_waitcnt lgkmcnt(5)
	v_mfma_f32_16x16x32_bf16 v[96:99], v[232:235], v[84:87], v[96:99]
	s_waitcnt lgkmcnt(4)
	v_mfma_f32_16x16x32_bf16 v[96:99], v[236:239], v[88:91], v[96:99]
	s_waitcnt lgkmcnt(2)
	v_mfma_f32_16x16x32_bf16 v[96:99], v[240:243], v[68:71], v[96:99]
	s_waitcnt lgkmcnt(0)
	v_mfma_f32_16x16x32_bf16 v[96:99], v[244:247], v[72:75], v[96:99]
	s_nop 7
	v_cvt_pk_bf16_f32 v96, v96, v97
	v_cvt_pk_bf16_f32 v97, v98, v99
	global_store_dwordx2 v[132:133], v[96:97], off offset:32
	s_cbranch_scc0 .LBB0_630
	v_add_u32_e32 v70, 0, v172
	v_cvt_pk_bf16_f32 v68, v12, v13
	v_cvt_pk_bf16_f32 v69, v14, v15
	v_add_u32_e32 v71, v70, v185
	s_waitcnt lgkmcnt(0)
	s_barrier
	ds_write_b64 v71, v[68:69] offset:60928
	v_cvt_pk_bf16_f32 v68, v16, v17
	v_cvt_pk_bf16_f32 v69, v18, v19
	ds_write_b64 v71, v[68:69] offset:65280
	v_cvt_pk_bf16_f32 v68, v24, v25
	v_cvt_pk_bf16_f32 v69, v26, v27
	v_add_u32_e32 v70, v70, v186
	ds_write_b64 v70, v[68:69] offset:60928
	v_cvt_pk_bf16_f32 v68, v32, v33
	v_cvt_pk_bf16_f32 v69, v34, v35
	v_add_u32_e32 v72, 0xee00, v71
	ds_write_b64 v70, v[68:69] offset:65280
	v_cvt_pk_bf16_f32 v68, v20, v21
	v_cvt_pk_bf16_f32 v69, v22, v23
	ds_write_b64 v72, v[68:69] offset:17408
	v_cvt_pk_bf16_f32 v68, v28, v29
	v_cvt_pk_bf16_f32 v69, v30, v31
	ds_write_b64 v72, v[68:69] offset:21760
	v_cvt_pk_bf16_f32 v68, v36, v37
	v_cvt_pk_bf16_f32 v69, v38, v39
	ds_write_b64 v72, v[68:69] offset:26112
	v_cvt_pk_bf16_f32 v68, v40, v41
	v_cvt_pk_bf16_f32 v69, v42, v43
	ds_write_b64 v72, v[68:69] offset:30464
	v_mov_b32_e32 v68, v164
	s_add_u32 s8, s8, 64
	v_ashrrev_i32_e32 v69, 4, v68
	v_add_u32_e32 v71, 32, v69
	v_lshrrev_b32_e32 v70, 6, v68
	v_lshrrev_b32_e32 v71, 2, v71
	v_and_b32_e32 v70, 14, v70
	v_and_b32_e32 v71, 14, v71
	v_add_lshl_u32 v70, v70, v68, 4
	v_add_lshl_u32 v71, v71, v68, 4
	v_lshlrev_b32_e32 v68, 4, v68
	v_mul_lo_u32 v72, v69, s20
	v_and_b32_e32 v68, 0xf0, v68
	v_add3_u32 v72, s60, v72, v68
	v_and_b32_e32 v70, 0xf0, v70
	s_waitcnt vmcnt(12)
	ds_write_b128 v72, v[52:55]
	s_waitcnt vmcnt(10)
	ds_write_b128 v72, v[64:67] offset:9216
	v_mul_lo_u32 v52, v69, s61
	v_add3_u32 v53, s66, v52, v70
	v_and_b32_e32 v71, 0xf0, v71
	ds_write_b128 v53, v[44:47]
	v_add_u32_e32 v44, 0x2200, v52
	v_add3_u32 v45, s66, v44, v71
	s_addc_u32 s9, s9, 0
	ds_write_b128 v45, v[48:51]
	v_add3_u32 v45, s64, v52, v68
	v_add3_u32 v44, s64, v44, v68
	s_cmp_eq_u32 s94, 16
	s_waitcnt vmcnt(9)
	ds_write_b128 v45, v[56:59]
	s_waitcnt vmcnt(8)
	ds_write_b128 v44, v[60:63]
	s_cbranch_scc0 .LBB0_606
	s_branch .LBB0_641
